# tok0_mix_dil tail: the (group,head) dot-product rounds of each wave issued together with interleaved reductions (was up to 3 serial rounds); placement preserved
# speedup vs baseline: 1.0108x; 1.0038x over previous
; DI void tok0_mix_dil(ldsp lds, const Params& p, const float* P, float* BRo, int task, int tid, int wid, int lane) {
;     ...
;     if (hm == 0) {
;         for (int pi = wid; pi < 18; pi += 8) {
;             const int g = pi / 6, head = pi - g * 6;
;             const float* qp = pr + g * 2304 + head * 128; const float* kp = qp + 768;
;             const float t = wave_sum(qp[lane] * kp[lane] + qp[64 + lane] * kp[64 + lane]) * 0.08838834764831845f;
;             if (lane == 0) S18[pi] = t;
;         }
;         __syncthreads();
.LBB0_124:
	s_cmp_lt_i32 s27, 2
	s_cselect_b32 s36, 1, 0
	s_mul_hi_i32 s22, s27, 0x2aaaaaab
	s_lshr_b32 s23, s22, 31
	s_add_i32 s30, s22, s23
	s_mul_i32 s22, s30, 0x900
	s_ashr_i32 s23, s22, 31
	s_lshl_b64 s[22:23], s[22:23], 2
	s_add_u32 s31, s54, s22
	s_mulk_i32 s30, 0xfd00
	s_addc_u32 s35, s55, s23
	s_add_i32 s22, s0, s30
	s_ashr_i32 s23, s22, 31
	s_lshl_b64 s[22:23], s[22:23], 2
	s_add_u32 s22, s31, s22
	s_addc_u32 s23, s35, s23
	s_mov_b64 s[98:99], s[22:23]
	s_add_i32 s27, s27, 8
	s_addk_i32 s0, 0x400
	s_mul_hi_i32 s22, s27, 0x2aaaaaab
	s_lshr_b32 s23, s22, 31
	s_add_i32 s30, s22, s23
	s_mul_i32 s22, s30, 0x900
	s_ashr_i32 s23, s22, 31
	s_lshl_b64 s[22:23], s[22:23], 2
	s_add_u32 s31, s54, s22
	s_mulk_i32 s30, 0xfd00
	s_addc_u32 s35, s55, s23
	s_add_i32 s22, s0, s30
	s_ashr_i32 s23, s22, 31
	s_lshl_b64 s[22:23], s[22:23], 2
	s_add_u32 s22, s31, s22
	s_addc_u32 s23, s35, s23
	s_mov_b64 s[100:101], s[22:23]
	s_add_i32 s27, s27, 8
	s_addk_i32 s0, 0x400
	s_mul_hi_i32 s22, s27, 0x2aaaaaab
	s_lshr_b32 s23, s22, 31
	s_add_i32 s30, s22, s23
	s_mul_i32 s22, s30, 0x900
	s_ashr_i32 s23, s22, 31
	s_lshl_b64 s[22:23], s[22:23], 2
	s_add_u32 s31, s54, s22
	s_mulk_i32 s30, 0xfd00
	s_addc_u32 s35, s55, s23
	s_add_i32 s22, s0, s30
	s_ashr_i32 s23, s22, 31
	s_lshl_b64 s[22:23], s[22:23], 2
	s_add_u32 s22, s31, s22
	s_addc_u32 s23, s35, s23
	s_cmp_lg_u32 s36, 0
	s_cselect_b64 s[22:23], s[22:23], s[100:101]
	s_waitcnt lgkmcnt(0)
	global_load_dword v0, v108, s[98:99] offset:3072
	global_load_dword v1, v108, s[98:99] offset:3328
	global_load_dword v2, v108, s[98:99] offset:256
	global_load_dword v3, v108, s[98:99]
	global_load_dword v4, v108, s[100:101] offset:3072
	global_load_dword v5, v108, s[100:101] offset:3328
	global_load_dword v6, v108, s[100:101] offset:256
	global_load_dword v7, v108, s[100:101]
	global_load_dword v8, v108, s[22:23] offset:3072
	global_load_dword v9, v108, s[22:23] offset:3328
	global_load_dword v10, v108, s[22:23] offset:256
	global_load_dword v11, v108, s[22:23]
	s_waitcnt vmcnt(0)
	v_mul_f32_e32 v1, v2, v1
	v_mul_f32_e32 v5, v6, v5
	v_mul_f32_e32 v9, v10, v9
	v_fmac_f32_e32 v1, v3, v0
	v_fmac_f32_e32 v5, v7, v4
	v_fmac_f32_e32 v9, v11, v8
	ds_bpermute_b32 v0, v95, v1
	ds_bpermute_b32 v4, v95, v5
	ds_bpermute_b32 v8, v95, v9
	s_waitcnt lgkmcnt(2)
	v_add_f32_e32 v0, v1, v0
	s_waitcnt lgkmcnt(1)
	v_add_f32_e32 v4, v5, v4
	s_waitcnt lgkmcnt(0)
	v_add_f32_e32 v8, v9, v8
	ds_bpermute_b32 v1, v96, v0
	ds_bpermute_b32 v5, v96, v4
	ds_bpermute_b32 v9, v96, v8
	s_waitcnt lgkmcnt(2)
	v_add_f32_e32 v0, v0, v1
	s_waitcnt lgkmcnt(1)
	v_add_f32_e32 v4, v4, v5
	s_waitcnt lgkmcnt(0)
	v_add_f32_e32 v8, v8, v9
	ds_bpermute_b32 v1, v97, v0
	ds_bpermute_b32 v5, v97, v4
	ds_bpermute_b32 v9, v97, v8
	s_waitcnt lgkmcnt(2)
	v_add_f32_e32 v0, v0, v1
	s_waitcnt lgkmcnt(1)
	v_add_f32_e32 v4, v4, v5
	s_waitcnt lgkmcnt(0)
	v_add_f32_e32 v8, v8, v9
	ds_bpermute_b32 v1, v98, v0
	ds_bpermute_b32 v5, v98, v4
	ds_bpermute_b32 v9, v98, v8
	s_waitcnt lgkmcnt(2)
	v_add_f32_e32 v0, v0, v1
	s_waitcnt lgkmcnt(1)
	v_add_f32_e32 v4, v4, v5
	s_waitcnt lgkmcnt(0)
	v_add_f32_e32 v8, v8, v9
	ds_bpermute_b32 v1, v99, v0
	ds_bpermute_b32 v5, v99, v4
	ds_bpermute_b32 v9, v99, v8
	s_waitcnt lgkmcnt(2)
	v_add_f32_e32 v0, v0, v1
	s_waitcnt lgkmcnt(1)
	v_add_f32_e32 v4, v4, v5
	s_waitcnt lgkmcnt(0)
	v_add_f32_e32 v8, v8, v9
	ds_bpermute_b32 v1, v100, v0
	ds_bpermute_b32 v5, v100, v4
	ds_bpermute_b32 v9, v100, v8
	s_waitcnt lgkmcnt(2)
	v_add_f32_e32 v0, v0, v1
	s_waitcnt lgkmcnt(1)
	v_add_f32_e32 v4, v4, v5
	s_waitcnt lgkmcnt(0)
	v_add_f32_e32 v8, v8, v9
	v_mul_f32_e32 v0, 0x3db504f3, v0
	v_mul_f32_e32 v4, 0x3db504f3, v4
	v_mul_f32_e32 v8, 0x3db504f3, v8
	s_add_i32 s30, s26, 32
	s_add_i32 s31, s26, 64
	s_and_saveexec_b64 s[22:23], s[40:41]
	v_mov_b32_e32 v1, s26
	ds_write_b32 v1, v0
	v_mov_b32_e32 v5, s30
	ds_write_b32 v5, v4
	s_cmp_eq_u32 s36, 0
	s_cbranch_scc1 .Ls5t_no3
	v_mov_b32_e32 v9, s31
	ds_write_b32 v9, v8
.Ls5t_no3:
	s_or_b64 exec, exec, s[22:23]
	s_branch .LBB0_120
	s_nop 0
	s_nop 0
	s_nop 0
	s_nop 0
	s_nop 0
	s_nop 0
	s_nop 0
	s_nop 0
	s_nop 0
	s_nop 0
	s_nop 0
	s_nop 0
